# v_f1 + waves 4-7 at s_setprio 1 for the second half of each attention tile (exp2..PV3)
# baseline (speedup 1.0000x reference)
.LBB0_983:
	v_readfirstlane_b32 s89, v184
	s_nop 0
	s_lshr_b32 s89, s89, 8
	s_mov_b32 s0, 0x20110
	s_addk_i32 s0, 0x100
	v_mov_b32_e32 v0, s0
	s_mov_b32 s0, 0x20114
	s_addk_i32 s0, 0x100
	ds_read_b32 v160, v0
	v_mov_b32_e32 v0, s0
	ds_read_b32 v161, v0
	s_load_dwordx2 s[92:93], s[94:95], 0xf8
	v_readlane_b32 s90, v254, 15
	s_and_b64 vcc, exec, s[68:69]
	s_movk_i32 s4, 0x100
	v_readlane_b32 s88, v254, 17
	v_readlane_b32 s91, v254, 16
	s_cbranch_vccnz .LBB0_1026
	v_and_b32_e32 v163, 31, v184
	v_mov_b32_e32 v2, 0x100
	v_bfe_u32 v1, v184, 5, 1
	v_lshl_add_u32 v169, v163, 7, v2
	v_lshrrev_b32_e32 v2, 1, v184
	v_bitop3_b32 v2, v1, v2, 7 bitop3:0x78
	v_lshlrev_b32_e32 v0, 3, v184
	v_lshlrev_b32_e32 v170, 4, v2
	v_lshlrev_b32_e32 v2, 1, v184
	v_and_b32_e32 v168, 24, v0
	v_and_b32_e32 v2, 32, v2
	v_add3_u32 v2, s4, v2, v168
	s_add_u32 s4, s46, 0xb200400
	s_load_dwordx2 s[8:9], s[94:95], 0x68
	s_addc_u32 s5, s47, 0
	v_lshlrev_b32_e32 v3, 4, v184
	s_add_u32 s52, s46, 0xb200800
	v_lshlrev_b32_e32 v0, 3, v1
	v_lshlrev_b32_e32 v1, 8, v1
	v_and_b32_e32 v3, 0xc0, v3
	s_addc_u32 s53, s47, 0
	v_mov_b32_e32 v157, 0
	v_add3_u32 v171, v2, v1, v3
	s_add_u32 s54, s46, 0xb308400
	v_lshlrev_b32_e32 v158, 1, v0
	v_mbcnt_lo_u32_b32 v0, -1, 0
	v_and_b32_e32 v162, 63, v184
	v_bfe_u32 v164, v184, 3, 3
	v_and_b32_e32 v165, 7, v184
	v_bfe_u32 v166, v184, 4, 2
	v_bfe_u32 v167, v184, 2, 4
	v_xor_b32_e32 v172, 32, v170
	v_xor_b32_e32 v173, 64, v170
	v_xor_b32_e32 v174, 0x60, v170
	v_add_u32_e32 v175, 0x1c000, v171
	v_add_u32_e32 v176, 0x1c200, v171
	v_add_u32_e32 v177, 0x1d000, v171
	v_add_u32_e32 v178, 0x1d200, v171
	v_add_u32_e32 v179, 0x1e000, v171
	v_add_u32_e32 v180, 0x1e200, v171
	v_add_u32_e32 v181, 0x1f000, v171
	v_add_u32_e32 v182, 0x1f200, v171
	v_add_u32_e32 v183, 0x1c400, v171
	v_add_u32_e32 v186, 0x1c600, v171
	v_add_u32_e32 v187, 0x1d400, v171
	v_add_u32_e32 v188, 0x1d600, v171
	v_add_u32_e32 v189, 0x1e400, v171
	v_add_u32_e32 v190, 0x1e600, v171
	v_add_u32_e32 v191, 0x1f400, v171
	v_add_u32_e32 v192, 0x1f600, v171
	v_add_u32_e32 v193, 0x1c800, v171
	v_add_u32_e32 v194, 0x1ca00, v171
	v_add_u32_e32 v195, 0x1d800, v171
	v_add_u32_e32 v196, 0x1da00, v171
	v_add_u32_e32 v197, 0x1e800, v171
	v_add_u32_e32 v198, 0x1ea00, v171
	v_add_u32_e32 v199, 0x1f800, v171
	v_add_u32_e32 v200, 0x1fa00, v171
	v_add_u32_e32 v201, 0x1cc00, v171
	v_add_u32_e32 v202, 0x1ce00, v171
	v_add_u32_e32 v203, 0x1dc00, v171
	v_add_u32_e32 v204, 0x1de00, v171
	v_add_u32_e32 v205, 0x1ec00, v171
	v_add_u32_e32 v206, 0x1ee00, v171
	v_add_u32_e32 v207, 0x1fc00, v171
	v_add_u32_e32 v208, 0x1fe00, v171
	s_addc_u32 s55, s47, 0
	s_lshl_b32 s60, s81, 5
	s_lshl_b32 s61, s56, 5
	v_mov_b32_e32 v159, v157
	v_mov_b32_e32 v209, 0x358637bd
	v_mbcnt_hi_u32_b32 v210, -1, v0
	s_branch .LBB0_986

.LBB0_1004:
	v_exp_f32_e32 v88, v88
	v_exp_f32_e32 v89, v89
	v_exp_f32_e32 v90, v90
	v_exp_f32_e32 v91, v91
	v_exp_f32_e32 v92, v92
	v_exp_f32_e32 v93, v93
	v_exp_f32_e32 v94, v94
	v_exp_f32_e32 v95, v95
	v_cvt_pk_bf16_f32 v88, v88, v89
	v_cvt_pk_bf16_f32 v89, v90, v91
	v_cvt_pk_bf16_f32 v90, v92, v93
	v_cvt_pk_bf16_f32 v91, v94, v95
	s_add_i32 s6, s87, 0x8000
	s_cmp_lg_u32 s6, 0x18000
	s_cselect_b32 s87, s6, 0
	s_add_i32 s6, s86, 0x8000
	s_waitcnt lgkmcnt(6)
	v_mfma_f32_32x32x16_bf16 v[48:63], v[88:91], v[100:103], v[48:63]
	s_cmp_lg_u32 s6, 0x18000
	s_cselect_b32 s86, s6, 0
	s_add_u32 s48, s48, 0x58000
	s_addc_u32 s49, s49, 0
	s_add_u32 s42, s42, 0x58000
	s_addc_u32 s43, s43, 0
	s_add_u32 s40, s40, 0x58000
	s_waitcnt lgkmcnt(4)
	v_mfma_f32_32x32x16_bf16 v[32:47], v[88:91], v[96:99], v[32:47]
	s_addc_u32 s41, s41, 0
	s_cmp_eq_u32 s84, s85
	s_waitcnt lgkmcnt(2)
	v_mfma_f32_32x32x16_bf16 v[16:31], v[88:91], v[84:87], v[16:31]
	s_waitcnt lgkmcnt(0)
	v_mfma_f32_32x32x16_bf16 v[0:15], v[88:91], v[80:83], v[0:15]
	v_mfma_f32_32x32x16_bf16 v[64:79], v[88:91], v[128:131], v[64:79]
	s_setprio 0
	s_cbranch_scc1 .LBB0_1017

.LBB0_1015:
	s_cmp_lg_u32 s89, 0
	s_cbranch_scc0 .Lhp_skip
	s_setprio 1
